# XCC-local barriers: invalidate at arrival and wait on the XCC arrival counter itself (no release hop); leader skips its release
# baseline (speedup 1.0000x reference)
; __device__ __forceinline__ unsigned xb_add(unsigned* p, unsigned v) { return __hip_atomic_fetch_add(p, v, __ATOMIC_RELAXED, __HIP_MEMORY_SCOPE_AGENT); }
; __device__ __forceinline__ void xcd_barrier(const XcdBarrier& b) {
;     ...
;         unsigned nloc = b.st[0], nx = b.st[1];
;         if (nloc == 0u) { xcd_barrier_complete(bar, b.x, nloc, nx); b.st[0] = nloc; b.st[1] = nx; }
;         const unsigned old = xb_add(&bar[XB_XSUB(b.x)], 1u);
.LBB0_451:
	s_cmp_eq_u32 s101, 1
	s_cbranch_scc0 .Lxl_noinv13239
	buffer_inv sc1

; __device__ __forceinline__ unsigned xb_ld(unsigned* p)              { return __hip_atomic_load(p, __ATOMIC_RELAXED, __HIP_MEMORY_SCOPE_AGENT); }
; __device__ __forceinline__ unsigned xb_add(unsigned* p, unsigned v) { return __hip_atomic_fetch_add(p, v, __ATOMIC_RELAXED, __HIP_MEMORY_SCOPE_AGENT); }
; #define XB_SPIN(cond, bar) do { unsigned _sp = 0; while (cond) { __builtin_amdgcn_s_sleep(1); \
;     if ((++_sp & 255u) == 0u) { if (xb_ld(&(bar)[XB_TMO])) break; if (_sp > XB_SPIN_CAP) { atomicAdd(&(bar)[XB_TMO], 1u); break; } } } } while (0)
; __device__ __forceinline__ void xcd_barrier(const XcdBarrier& b) {
;     ...
;         const unsigned old = xb_add(&bar[XB_XSUB(b.x)], 1u);
;         const unsigned gen = old / nloc;
;         if (old + 1u == (gen + 1u) * nloc) {
;             __builtin_amdgcn_fence(__ATOMIC_RELEASE, "agent");
;             asm volatile("s_waitcnt vmcnt(0)" ::: "memory");
;             const unsigned og = xb_add(&bar[XB_TOP], 1u);
;             const unsigned tg = og / nx;
;             if (og + 1u == (tg + 1u) * nx) xb_add(&bar[XB_TOPGEN], 1u);
;             else XB_SPIN(xb_ld(&bar[XB_TOPGEN]) == tg, bar);
;             __builtin_amdgcn_fence(__ATOMIC_ACQUIRE, "agent");
;             xb_add(&bar[XB_XGEN(b.x)], 1u);
;             asm volatile("s_waitcnt vmcnt(0)" ::: "memory");
;         } else {
;             XB_SPIN(xb_ld(&bar[XB_XGEN(b.x)]) == gen, bar);
;             __builtin_amdgcn_fence(__ATOMIC_ACQUIRE, "agent");
;             asm volatile("s_waitcnt vmcnt(0)" ::: "memory");
;         }
.LBB0_453:
	s_or_b64 exec, exec, s[12:13]
	v_cvt_f32_u32_e32 v4, v2
	s_waitcnt vmcnt(0)
	v_readfirstlane_b32 s8, v3
	v_sub_u32_e32 v3, 0, v2
	v_rcp_iflag_f32_e32 v4, v4
	v_add_u32_e32 v5, s8, v1
	v_mul_f32_e32 v4, 0x4f7ffffe, v4
	v_cvt_u32_f32_e32 v4, v4
	v_mul_lo_u32 v1, v3, v4
	v_mul_hi_u32 v1, v4, v1
	v_add_u32_e32 v1, v4, v1
	v_mul_hi_u32 v1, v5, v1
	v_mul_lo_u32 v3, v1, v2
	v_sub_u32_e32 v3, v5, v3
	v_add_u32_e32 v4, 1, v1
	v_cmp_ge_u32_e32 vcc, v3, v2
	s_nop 1
	v_cndmask_b32_e32 v1, v1, v4, vcc
	v_sub_u32_e32 v4, v3, v2
	v_cndmask_b32_e32 v3, v3, v4, vcc
	v_add_u32_e32 v4, 1, v1
	v_cmp_ge_u32_e32 vcc, v3, v2
	v_add_u32_e32 v3, 1, v5
	s_nop 0
	v_cndmask_b32_e32 v1, v1, v4, vcc
	v_mul_lo_u32 v4, v2, v1
	v_add_u32_e32 v2, v4, v2
	v_cmp_ne_u32_e32 vcc, v3, v2
	s_and_saveexec_b64 s[8:9], vcc
	s_xor_b64 s[8:9], exec, s[8:9]
	s_cbranch_execz .LBB0_467
	s_waitcnt lgkmcnt(0)
	s_cmp_eq_u32 s101, 1
	s_cbranch_scc1 .Lxl_loc13239
	buffer_inv sc1
	v_add_u32_e32 v2, 1, v1
	s_add_u32 s16, s6, 0x2400
	s_addc_u32 s17, s7, 0
	s_branch .Lxl_go13239
.Lxl_loc13239:
	s_add_u32 s16, s6, 0x1400
	s_addc_u32 s17, s7, 0
.Lxl_go13239:
	v_mov_b32_e32 v1, v2
	v_mov_b32_e32 v0, 0
	global_load_dword v0, v0, s[16:17] sc1
	s_waitcnt vmcnt(0)
	v_cmp_lt_u32_e32 vcc, v0, v1
	s_and_saveexec_b64 s[12:13], vcc
	s_cbranch_execz .LBB0_466
	s_add_u32 s14, s58, 0xc0200
	s_addc_u32 s15, s59, 0
	s_mov_b32 s28, 1
	s_mov_b64 s[18:19], 0
	v_mov_b32_e32 v0, 0
	s_branch .LBB0_457

; __device__ __forceinline__ unsigned xb_add(unsigned* p, unsigned v) { return __hip_atomic_fetch_add(p, v, __ATOMIC_RELAXED, __HIP_MEMORY_SCOPE_AGENT); }
; __device__ __forceinline__ void xcd_barrier(const XcdBarrier& b) {
;     ...
;         if (old + 1u == (gen + 1u) * nloc) {
;             __builtin_amdgcn_fence(__ATOMIC_RELEASE, "agent");
;             asm volatile("s_waitcnt vmcnt(0)" ::: "memory");
;             const unsigned og = xb_add(&bar[XB_TOP], 1u);
;             const unsigned tg = og / nx;
;             if (og + 1u == (tg + 1u) * nx) xb_add(&bar[XB_TOPGEN], 1u);
.LBB0_467:
	s_andn2_saveexec_b64 s[8:9], s[8:9]
	s_cbranch_execz .LBB0_487
	s_mov_b64 s[8:9], exec
	s_cmp_eq_u32 s101, 1
	s_cbranch_scc1 .LBB0_487
	buffer_inv sc1
	buffer_wbl2 sc1
	s_waitcnt lgkmcnt(0)
	s_waitcnt vmcnt(0)
	v_mbcnt_lo_u32_b32 v1, s8, 0
	v_mbcnt_hi_u32_b32 v1, s9, v1
	v_cmp_eq_u32_e32 vcc, 0, v1
	s_and_saveexec_b64 s[12:13], vcc
	s_cbranch_execz .LBB0_470
	s_bcnt1_i32_b64 s8, s[8:9]
	v_mov_b32_e32 v2, 0xc3000
	v_mov_b32_e32 v3, s8
	global_atomic_add v2, v2, v3, s[58:59] offset:1024 sc0

; __device__ __forceinline__ unsigned xb_ld(unsigned* p)              { return __hip_atomic_load(p, __ATOMIC_RELAXED, __HIP_MEMORY_SCOPE_AGENT); }
; __device__ __forceinline__ unsigned xb_add(unsigned* p, unsigned v) { return __hip_atomic_fetch_add(p, v, __ATOMIC_RELAXED, __HIP_MEMORY_SCOPE_AGENT); }
; #define XB_SPIN(cond, bar) do { unsigned _sp = 0; while (cond) { __builtin_amdgcn_s_sleep(1); \
;     if ((++_sp & 255u) == 0u) { if (xb_ld(&(bar)[XB_TMO])) break; if (_sp > XB_SPIN_CAP) { atomicAdd(&(bar)[XB_TMO], 1u); break; } } } } while (0)
; __device__ __forceinline__ void xcd_barrier(const XcdBarrier& b) {
;     ...
;         const unsigned old = xb_add(&bar[XB_XSUB(b.x)], 1u);
;         const unsigned gen = old / nloc;
;         if (old + 1u == (gen + 1u) * nloc) {
;             __builtin_amdgcn_fence(__ATOMIC_RELEASE, "agent");
;             asm volatile("s_waitcnt vmcnt(0)" ::: "memory");
;             const unsigned og = xb_add(&bar[XB_TOP], 1u);
;             const unsigned tg = og / nx;
;             if (og + 1u == (tg + 1u) * nx) xb_add(&bar[XB_TOPGEN], 1u);
;             else XB_SPIN(xb_ld(&bar[XB_TOPGEN]) == tg, bar);
;             __builtin_amdgcn_fence(__ATOMIC_ACQUIRE, "agent");
;             xb_add(&bar[XB_XGEN(b.x)], 1u);
;             asm volatile("s_waitcnt vmcnt(0)" ::: "memory");
;         } else {
;             XB_SPIN(xb_ld(&bar[XB_XGEN(b.x)]) == gen, bar);
;             __builtin_amdgcn_fence(__ATOMIC_ACQUIRE, "agent");
;             asm volatile("s_waitcnt vmcnt(0)" ::: "memory");
;         }
.LBB0_529:
	s_or_b64 exec, exec, s[10:11]
	v_cvt_f32_u32_e32 v4, v2
	s_waitcnt vmcnt(0)
	v_readfirstlane_b32 s6, v3
	v_sub_u32_e32 v3, 0, v2
	v_rcp_iflag_f32_e32 v4, v4
	v_add_u32_e32 v5, s6, v1
	v_mul_f32_e32 v4, 0x4f7ffffe, v4
	v_cvt_u32_f32_e32 v4, v4
	v_mul_lo_u32 v1, v3, v4
	v_mul_hi_u32 v1, v4, v1
	v_add_u32_e32 v1, v4, v1
	v_mul_hi_u32 v1, v5, v1
	v_mul_lo_u32 v3, v1, v2
	v_sub_u32_e32 v3, v5, v3
	v_add_u32_e32 v4, 1, v1
	v_cmp_ge_u32_e32 vcc, v3, v2
	s_nop 1
	v_cndmask_b32_e32 v1, v1, v4, vcc
	v_sub_u32_e32 v4, v3, v2
	v_cndmask_b32_e32 v3, v3, v4, vcc
	v_add_u32_e32 v4, 1, v1
	v_cmp_ge_u32_e32 vcc, v3, v2
	v_add_u32_e32 v3, 1, v5
	s_nop 0
	v_cndmask_b32_e32 v1, v1, v4, vcc
	v_mul_lo_u32 v4, v2, v1
	v_add_u32_e32 v2, v4, v2
	v_cmp_ne_u32_e32 vcc, v3, v2
	s_and_saveexec_b64 s[6:7], vcc
	s_xor_b64 s[6:7], exec, s[6:7]
	s_cbranch_execz .LBB0_543
	s_waitcnt lgkmcnt(0)
	s_cmp_eq_u32 s101, 1
	s_cbranch_scc1 .Lxl_loc15862
	buffer_inv sc1
	v_add_u32_e32 v2, 1, v1
	s_add_u32 s14, s4, 0x2400
	s_addc_u32 s15, s5, 0
	s_branch .Lxl_go15862
.Lxl_loc15862:
	s_add_u32 s14, s4, 0x1400
	s_addc_u32 s15, s5, 0
.Lxl_go15862:
	v_mov_b32_e32 v1, v2
	v_mov_b32_e32 v0, 0
	global_load_dword v0, v0, s[14:15] sc1
	s_waitcnt vmcnt(0)
	v_cmp_lt_u32_e32 vcc, v0, v1
	s_and_saveexec_b64 s[10:11], vcc
	s_cbranch_execz .LBB0_542
	s_add_u32 s12, s58, 0xc0200
	s_addc_u32 s13, s59, 0
	s_mov_b32 s26, 1
	s_mov_b64 s[16:17], 0
	v_mov_b32_e32 v0, 0
	s_branch .LBB0_533

; __device__ __forceinline__ unsigned xb_ld(unsigned* p)              { return __hip_atomic_load(p, __ATOMIC_RELAXED, __HIP_MEMORY_SCOPE_AGENT); }
; #define XB_SPIN(cond, bar) do { unsigned _sp = 0; while (cond) { __builtin_amdgcn_s_sleep(1); \
;     if ((++_sp & 255u) == 0u) { if (xb_ld(&(bar)[XB_TMO])) break; if (_sp > XB_SPIN_CAP) { atomicAdd(&(bar)[XB_TMO], 1u); break; } } } } while (0)
; __device__ __forceinline__ void xcd_barrier(const XcdBarrier& b) {
;     ...
;             XB_SPIN(xb_ld(&bar[XB_XGEN(b.x)]) == gen, bar);
.LBB0_537:
	global_load_dword v2, v0, s[14:15] sc1
	s_add_i32 s26, s26, 1
	s_mov_b64 s[22:23], -1
	s_waitcnt vmcnt(0)
	v_cmp_ge_u32_e32 vcc, v2, v1
	s_orn2_b64 s[20:21], vcc, exec
	s_branch .LBB0_532

; __device__ __forceinline__ unsigned xb_add(unsigned* p, unsigned v) { return __hip_atomic_fetch_add(p, v, __ATOMIC_RELAXED, __HIP_MEMORY_SCOPE_AGENT); }
; __device__ __forceinline__ void xcd_barrier(const XcdBarrier& b) {
;     ...
;         if (old + 1u == (gen + 1u) * nloc) {
;             __builtin_amdgcn_fence(__ATOMIC_RELEASE, "agent");
;             asm volatile("s_waitcnt vmcnt(0)" ::: "memory");
;             const unsigned og = xb_add(&bar[XB_TOP], 1u);
;             const unsigned tg = og / nx;
;             if (og + 1u == (tg + 1u) * nx) xb_add(&bar[XB_TOPGEN], 1u);
.LBB0_543:
	s_andn2_saveexec_b64 s[6:7], s[6:7]
	s_cbranch_execz .LBB0_563
	s_mov_b64 s[6:7], exec
	s_cmp_eq_u32 s101, 1
	s_cbranch_scc1 .LBB0_563
	buffer_inv sc1
	buffer_wbl2 sc1
	s_waitcnt lgkmcnt(0)
	s_waitcnt vmcnt(0)
	v_mbcnt_lo_u32_b32 v1, s6, 0
	v_mbcnt_hi_u32_b32 v1, s7, v1
	v_cmp_eq_u32_e32 vcc, 0, v1
	s_and_saveexec_b64 s[10:11], vcc
	s_cbranch_execz .LBB0_546
	s_bcnt1_i32_b64 s6, s[6:7]
	v_mov_b32_e32 v2, 0xc3000
	v_mov_b32_e32 v3, s6
	global_atomic_add v2, v2, v3, s[58:59] offset:1024 sc0

; __device__ __forceinline__ unsigned xb_ld(unsigned* p)              { return __hip_atomic_load(p, __ATOMIC_RELAXED, __HIP_MEMORY_SCOPE_AGENT); }
; __device__ __forceinline__ unsigned xb_add(unsigned* p, unsigned v) { return __hip_atomic_fetch_add(p, v, __ATOMIC_RELAXED, __HIP_MEMORY_SCOPE_AGENT); }
; #define XB_SPIN(cond, bar) do { unsigned _sp = 0; while (cond) { __builtin_amdgcn_s_sleep(1); \
;     if ((++_sp & 255u) == 0u) { if (xb_ld(&(bar)[XB_TMO])) break; if (_sp > XB_SPIN_CAP) { atomicAdd(&(bar)[XB_TMO], 1u); break; } } } } while (0)
; __device__ __forceinline__ void xcd_barrier(const XcdBarrier& b) {
;     ...
;         const unsigned old = xb_add(&bar[XB_XSUB(b.x)], 1u);
;         const unsigned gen = old / nloc;
;         if (old + 1u == (gen + 1u) * nloc) {
;             __builtin_amdgcn_fence(__ATOMIC_RELEASE, "agent");
;             asm volatile("s_waitcnt vmcnt(0)" ::: "memory");
;             const unsigned og = xb_add(&bar[XB_TOP], 1u);
;             const unsigned tg = og / nx;
;             if (og + 1u == (tg + 1u) * nx) xb_add(&bar[XB_TOPGEN], 1u);
;             else XB_SPIN(xb_ld(&bar[XB_TOPGEN]) == tg, bar);
;             __builtin_amdgcn_fence(__ATOMIC_ACQUIRE, "agent");
;             xb_add(&bar[XB_XGEN(b.x)], 1u);
;             asm volatile("s_waitcnt vmcnt(0)" ::: "memory");
;         } else {
;             XB_SPIN(xb_ld(&bar[XB_XGEN(b.x)]) == gen, bar);
.LBB0_691:
	s_or_b64 exec, exec, s[12:13]
	v_cvt_f32_u32_e32 v4, v2
	s_waitcnt vmcnt(0)
	v_readfirstlane_b32 s3, v3
	v_sub_u32_e32 v3, 0, v2
	v_rcp_iflag_f32_e32 v4, v4
	v_add_u32_e32 v5, s3, v1
	v_mul_f32_e32 v4, 0x4f7ffffe, v4
	v_cvt_u32_f32_e32 v4, v4
	v_mul_lo_u32 v1, v3, v4
	v_mul_hi_u32 v1, v4, v1
	v_add_u32_e32 v1, v4, v1
	v_mul_hi_u32 v1, v5, v1
	v_mul_lo_u32 v3, v1, v2
	v_sub_u32_e32 v3, v5, v3
	v_add_u32_e32 v4, 1, v1
	v_cmp_ge_u32_e32 vcc, v3, v2
	s_nop 1
	v_cndmask_b32_e32 v1, v1, v4, vcc
	v_sub_u32_e32 v4, v3, v2
	v_cndmask_b32_e32 v3, v3, v4, vcc
	v_add_u32_e32 v4, 1, v1
	v_cmp_ge_u32_e32 vcc, v3, v2
	v_add_u32_e32 v3, 1, v5
	s_nop 0
	v_cndmask_b32_e32 v1, v1, v4, vcc
	v_mul_lo_u32 v4, v2, v1
	v_add_u32_e32 v2, v4, v2
	v_cmp_ne_u32_e32 vcc, v3, v2
	s_and_saveexec_b64 s[10:11], vcc
	s_xor_b64 s[10:11], exec, s[10:11]
	s_cbranch_execz .LBB0_705
	s_waitcnt lgkmcnt(0)
	s_cmp_eq_u32 s101, 1
	s_cbranch_scc1 .Lxl_loc19923
	buffer_inv sc1
	v_add_u32_e32 v2, 1, v1
	s_add_u32 s16, s6, 0x2400
	s_addc_u32 s17, s7, 0
	s_branch .Lxl_go19923

; __device__ __forceinline__ unsigned xb_ld(unsigned* p)              { return __hip_atomic_load(p, __ATOMIC_RELAXED, __HIP_MEMORY_SCOPE_AGENT); }
; #define XB_SPIN(cond, bar) do { unsigned _sp = 0; while (cond) { __builtin_amdgcn_s_sleep(1); \
;     if ((++_sp & 255u) == 0u) { if (xb_ld(&(bar)[XB_TMO])) break; if (_sp > XB_SPIN_CAP) { atomicAdd(&(bar)[XB_TMO], 1u); break; } } } } while (0)
; __device__ __forceinline__ void xcd_barrier(const XcdBarrier& b) {
;     ...
;             XB_SPIN(xb_ld(&bar[XB_XGEN(b.x)]) == gen, bar);
;             __builtin_amdgcn_fence(__ATOMIC_ACQUIRE, "agent");
;             asm volatile("s_waitcnt vmcnt(0)" ::: "memory");
.Lxl_go19923:
	v_mov_b32_e32 v1, v2
	v_mov_b32_e32 v0, 0
	global_load_dword v0, v0, s[16:17] sc1
	s_waitcnt vmcnt(0)
	v_cmp_lt_u32_e32 vcc, v0, v1
	s_and_saveexec_b64 s[12:13], vcc
	s_cbranch_execz .LBB0_704
	s_add_u32 s14, s58, 0xc0200
	s_addc_u32 s15, s59, 0
	s_mov_b32 s3, 1
	s_mov_b64 s[18:19], 0
	v_mov_b32_e32 v0, 0
	s_branch .LBB0_695

; __device__ __forceinline__ unsigned xb_ld(unsigned* p)              { return __hip_atomic_load(p, __ATOMIC_RELAXED, __HIP_MEMORY_SCOPE_AGENT); }
; #define XB_SPIN(cond, bar) do { unsigned _sp = 0; while (cond) { __builtin_amdgcn_s_sleep(1); \
;     if ((++_sp & 255u) == 0u) { if (xb_ld(&(bar)[XB_TMO])) break; if (_sp > XB_SPIN_CAP) { atomicAdd(&(bar)[XB_TMO], 1u); break; } } } } while (0)
; __device__ __forceinline__ void xcd_barrier(const XcdBarrier& b) {
;     ...
;             XB_SPIN(xb_ld(&bar[XB_XGEN(b.x)]) == gen, bar);
.LBB0_699:
	global_load_dword v2, v0, s[16:17] sc1
	s_add_i32 s3, s3, 1
	s_mov_b64 s[24:25], -1
	s_waitcnt vmcnt(0)
	v_cmp_ge_u32_e32 vcc, v2, v1
	s_orn2_b64 s[22:23], vcc, exec
	s_branch .LBB0_694

; __device__ __forceinline__ unsigned xb_add(unsigned* p, unsigned v) { return __hip_atomic_fetch_add(p, v, __ATOMIC_RELAXED, __HIP_MEMORY_SCOPE_AGENT); }
; __device__ __forceinline__ void xcd_barrier(const XcdBarrier& b) {
;     ...
;         if (old + 1u == (gen + 1u) * nloc) {
;             __builtin_amdgcn_fence(__ATOMIC_RELEASE, "agent");
;             asm volatile("s_waitcnt vmcnt(0)" ::: "memory");
;             const unsigned og = xb_add(&bar[XB_TOP], 1u);
;             const unsigned tg = og / nx;
;             if (og + 1u == (tg + 1u) * nx) xb_add(&bar[XB_TOPGEN], 1u);
.LBB0_705:
	s_andn2_saveexec_b64 s[10:11], s[10:11]
	s_cbranch_execz .LBB0_725
	s_mov_b64 s[10:11], exec
	s_cmp_eq_u32 s101, 1
	s_cbranch_scc1 .LBB0_725
	buffer_inv sc1
	buffer_wbl2 sc1
	s_waitcnt lgkmcnt(0)
	s_waitcnt vmcnt(0)
	v_mbcnt_lo_u32_b32 v1, s10, 0
	v_mbcnt_hi_u32_b32 v1, s11, v1
	v_cmp_eq_u32_e32 vcc, 0, v1
	s_and_saveexec_b64 s[12:13], vcc
	s_cbranch_execz .LBB0_708
	s_bcnt1_i32_b64 s3, s[10:11]
	v_mov_b32_e32 v2, 0xc3000
	v_mov_b32_e32 v3, s3
	global_atomic_add v2, v2, v3, s[58:59] offset:1024 sc0
